# NSA unit queue: grab for the next unit issued at the start of the current unit and collected into a spare SGPR, so the atomic round trip is off the path between units
# baseline (speedup 1.0000x reference)
; #define LAS __attribute__((address_space(3)))
; __device__ __forceinline__ unsigned f2bf(float f) { unsigned u = __float_as_uint(f); return (u + 0x7fffu + ((u >> 16) & 1u)) >> 16; }
; __device__ __forceinline__ int hw_lane() { int ln; asm volatile("v_mbcnt_lo_u32_b32 %0, -1, 0\n\tv_mbcnt_hi_u32_b32 %0, -1, %0" : "=v"(ln)); return ln; }
; __device__ __forceinline__ Ctx relaunder(const Ctx& c0) { Ctx c = c0; int w = c0.wave; asm volatile("" : "+s"(w) :: "memory"); int ln = hw_lane(); asm volatile("" : "+v"(ln) :: "memory"); c.wave = w; c.lane = ln; c.tid = w * 64 + ln; int b = c0.bid; asm volatile("" : "+s"(b) :: "memory"); c.bid = b; return c; }
; __device__ __forceinline__ int crow(int r, int hi) { return (r & 3) + 8 * (r >> 2) + 4 * hi; }
; __device__ __forceinline__ float halves_sum(float v) { auto rr = __builtin_amdgcn_permlane32_swap(__float_as_uint(v), __float_as_uint(v), false, false); return __uint_as_float(rr[0]) + __uint_as_float(rr[1]); }
; __device__ __forceinline__ void nsa_unit(const Ctx& c, int l, int b, int n, int qt) {
;     ...
;         const float ltot = halves_sum(st.l); nsa_fold(of0, of1, st.o0, st.o1, ltot > 0.f ? gate2 / ltot : 0.f, wsf, r32, hi);
;     }
;     __builtin_amdgcn_s_setprio(0);
;     {
;         LAS bf16* stg = (LAS bf16*)(lds + NL_IMP + wid * 4096);
; #pragma unroll
;         for (int r = 0; r < 16; ++r) { const int orow = crow(r, hi); stg[orow * 64 + r32] = (bf16)f2bf(of0[r]); stg[orow * 64 + 32 + r32] = (bf16)f2bf(of1[r]); }
;     ...
;         const Ctx c = relaunder(c0);
;         volatile LAS unsigned* slot = (volatile LAS unsigned*)(c.lds - CTLB + MISC_OFF + 64);
;         for (;;) {
;             if (c.wave == 0 && hw_lane() == 0) { unsigned* head = c.ctl + (l ? CW_U1 : CW_U0) + rep * 1024; *slot = __hip_atomic_fetch_add(head, 1u, __ATOMIC_RELAXED, __HIP_MEMORY_SCOPE_AGENT); }
;             __syncthreads();
;             const unsigned u = *slot;
;             __syncthreads();
;             if (u >= 512u) break;
;             Ctx cu = c; { int ln = hw_lane(); asm volatile("" : "+v"(ln)); cu.lane = ln; cu.tid = cu.wave * 64 + ln; }
;             nsa_unit(cu, l, (int)(u >> 1) & 3, (int)u & 1, 63 - (int)(u >> 3));
.LBB0_1296:
	v_readlane_b32 s2, v254, 46
	v_mbcnt_lo_u32_b32 v0, -1, 0
	v_mbcnt_hi_u32_b32 v0, -1, v0
	v_readlane_b32 s0, v253, 17
	s_cmp_eq_u32 s2, 0
	v_readlane_b32 s0, v255, 10
	s_cselect_b64 s[38:39], -1, 0
	s_lshl_b32 s30, s0, 10
	s_lshl_b64 s[4:5], s[30:31], 2
	v_readlane_b32 s0, v255, 0
	s_add_u32 s6, s0, s4
	v_readlane_b32 s0, v254, 52
	v_writelane_b32 v255, s4, 18
	s_addc_u32 s7, s0, s5
	s_lshl_b32 s0, s2, 5
	v_writelane_b32 v255, s5, 19
	s_ashr_i32 s4, s2, 1
	s_and_b32 s33, s0, 32
	v_writelane_b32 v255, s6, 16
	s_cmp_gt_i32 s2, 3
	s_cselect_b64 s[0:1], -1, 0
	v_writelane_b32 v255, s7, 17
	v_writelane_b32 v255, s0, 12
	s_lshl_b32 s3, s2, 4
	s_and_b32 s22, s3, 48
	v_writelane_b32 v255, s1, 13
	s_lshl_b32 s0, s2, 8
	s_lshl_b32 s3, s2, 10
	s_add_i32 s0, s0, 0
	s_lshl_b32 s1, s2, 3
	s_add_i32 s26, s3, 0
	s_lshl_b32 s3, s4, 6
	s_mulk_i32 s2, 0xc00
	s_add_i32 s0, s0, 0x18a00
	s_and_b32 s23, s1, 0xffffffe0
	v_writelane_b32 v254, s4, 62
	v_writelane_b32 v255, s3, 14
	s_add_i32 s18, s26, s2
	s_andn2_b64 vcc, exec, s[38:39]
	s_cbranch_vccnz .Lnq_skip0
	v_mbcnt_lo_u32_b32 v0, -1, 0
	v_mbcnt_hi_u32_b32 v0, -1, v0
	v_cmp_eq_u32_e32 vcc, 0, v0
	s_and_saveexec_b64 s[2:3], vcc
	v_mov_b32_e32 v2, 1
	global_atomic_add v2, v1, v2, s[6:7] sc0
	s_waitcnt vmcnt(0)
	s_or_b64 exec, exec, s[2:3]
	v_readfirstlane_b32 s32, v2
.Lnq_skip0:
	s_branch .LBB0_1299
.LBB0_1297:
	s_or_b64 exec, exec, s[2:3]
	s_waitcnt lgkmcnt(0)
	ds_read_b128 v[2:5], v239
	ds_read_b128 v[6:9], v239 offset:32
	v_fma_f32 v39, v39, v199, 0
	v_fma_f32 v23, v23, v199, 0
	v_fma_f32 v38, v38, v198, 0
	v_fma_f32 v22, v22, v198, 0
	v_fma_f32 v37, v37, v197, 0
	v_fma_f32 v21, v21, v197, 0
	v_fma_f32 v36, v36, v196, 0
	v_fma_f32 v20, v20, v196, 0
	v_fma_f32 v35, v35, v195, 0
	v_fma_f32 v19, v19, v195, 0
	v_fma_f32 v34, v34, v194, 0
	v_fma_f32 v18, v18, v194, 0
	v_fma_f32 v33, v33, v193, 0
	v_fma_f32 v17, v17, v193, 0
	v_fma_f32 v32, v32, v192, 0
	v_fma_f32 v16, v16, v192, 0
	v_fmac_f32_e32 v39, v55, v215
	v_fmac_f32_e32 v23, v71, v215
	v_fmac_f32_e32 v38, v54, v214
	v_fmac_f32_e32 v22, v70, v214
	v_fmac_f32_e32 v37, v53, v213
	v_fmac_f32_e32 v21, v69, v213
	v_fmac_f32_e32 v36, v52, v212
	v_fmac_f32_e32 v20, v68, v212
	v_fmac_f32_e32 v35, v51, v211
	v_fmac_f32_e32 v19, v67, v211
	v_fmac_f32_e32 v34, v50, v210
	v_fmac_f32_e32 v18, v66, v210
	v_fmac_f32_e32 v33, v49, v209
	v_fmac_f32_e32 v17, v65, v209
	v_fmac_f32_e32 v32, v48, v208
	v_fmac_f32_e32 v16, v64, v208
	s_waitcnt lgkmcnt(1)
	v_fmac_f32_e32 v16, v96, v2
	v_fmac_f32_e32 v32, v80, v2
	v_fmac_f32_e32 v17, v97, v3
	v_fmac_f32_e32 v33, v81, v3
	v_fmac_f32_e32 v18, v98, v4
	v_fmac_f32_e32 v34, v82, v4
	v_fmac_f32_e32 v19, v99, v5
	v_fmac_f32_e32 v35, v83, v5
	s_waitcnt lgkmcnt(0)
	v_fmac_f32_e32 v20, v100, v6
	v_fmac_f32_e32 v36, v84, v6
	v_fmac_f32_e32 v21, v101, v7
	v_fmac_f32_e32 v37, v85, v7
	v_fmac_f32_e32 v22, v102, v8
	ds_read_b128 v[2:5], v239 offset:64
	v_fmac_f32_e32 v38, v86, v8
	v_fmac_f32_e32 v23, v103, v9
	v_fmac_f32_e32 v39, v87, v9
	ds_read_b128 v[6:9], v239 offset:96
	v_fma_f32 v0, v47, v207, 0
	v_fma_f32 v10, v31, v207, 0
	v_fma_f32 v11, v46, v206, 0
	v_fma_f32 v12, v30, v206, 0
	v_fma_f32 v13, v45, v205, 0
	v_fma_f32 v14, v29, v205, 0
	v_fma_f32 v15, v44, v204, 0
	v_fma_f32 v28, v28, v204, 0
	v_fma_f32 v29, v43, v203, 0
	v_fma_f32 v27, v27, v203, 0
	v_fma_f32 v30, v42, v202, 0
	v_fma_f32 v26, v26, v202, 0
	v_fma_f32 v31, v41, v201, 0
	v_fma_f32 v25, v25, v201, 0
	v_fma_f32 v40, v40, v200, 0
	v_fma_f32 v24, v24, v200, 0
	v_fmac_f32_e32 v0, v63, v223
	v_fmac_f32_e32 v10, v79, v223
	v_fmac_f32_e32 v11, v62, v222
	v_fmac_f32_e32 v12, v78, v222
	v_fmac_f32_e32 v13, v61, v221
	v_fmac_f32_e32 v14, v77, v221
	v_fmac_f32_e32 v15, v60, v220
	v_fmac_f32_e32 v28, v76, v220
	v_fmac_f32_e32 v29, v59, v219
	v_fmac_f32_e32 v27, v75, v219
	v_fmac_f32_e32 v30, v58, v218
	v_fmac_f32_e32 v26, v74, v218
	v_fmac_f32_e32 v31, v57, v217
	v_fmac_f32_e32 v25, v73, v217
	v_fmac_f32_e32 v40, v56, v216
	v_fmac_f32_e32 v24, v72, v216
	s_waitcnt lgkmcnt(1)
	v_fmac_f32_e32 v24, v104, v2
	v_fmac_f32_e32 v40, v88, v2
	v_fmac_f32_e32 v25, v105, v3
	v_fmac_f32_e32 v31, v89, v3
	v_fmac_f32_e32 v26, v106, v4
	v_fmac_f32_e32 v30, v90, v4
	v_fmac_f32_e32 v27, v107, v5
	v_fmac_f32_e32 v29, v91, v5
	s_waitcnt lgkmcnt(0)
; #define LAS __attribute__((address_space(3)))
; __device__ __forceinline__ unsigned f2bf(float f) { unsigned u = __float_as_uint(f); return (u + 0x7fffu + ((u >> 16) & 1u)) >> 16; }
; __device__ __forceinline__ void wave_lds_sync() { asm volatile("s_waitcnt lgkmcnt(0)" ::: "memory"); }
; __device__ __forceinline__ int crow(int r, int hi) { return (r & 3) + 8 * (r >> 2) + 4 * hi; }
; __device__ __forceinline__ void nsa_unit(const Ctx& c, int l, int b, int n, int qt) {
;     ...
;     __builtin_amdgcn_s_setprio(0);
;     {
;         LAS bf16* stg = (LAS bf16*)(lds + NL_IMP + wid * 4096);
; #pragma unroll
;         for (int r = 0; r < 16; ++r) { const int orow = crow(r, hi); stg[orow * 64 + r32] = (bf16)f2bf(of0[r]); stg[orow * 64 + 32 + r32] = (bf16)f2bf(of1[r]); }
;         wave_lds_sync();
;         bf16* MIX = (bf16*)(AWS + WS_MIX) + (rowbase + t0 + th * 32) * DM + hq * 64;
; #pragma unroll
;         for (int i = 0; i < 4; ++i) { const int row = i * 8 + (lane >> 3), ch = lane & 7; const u32x4 v = *(const LAS u32x4*)(stg + row * 64 + ch * 8); *(u32x4*)(MIX + (size_t)row * DM + ch * 8) = v; }
;     }
;     __syncthreads();
	v_fmac_f32_e32 v28, v108, v6
	v_fmac_f32_e32 v15, v92, v6
	v_fmac_f32_e32 v14, v109, v7
	v_fmac_f32_e32 v13, v93, v7
	v_fmac_f32_e32 v12, v110, v8
	v_fmac_f32_e32 v11, v94, v8
	v_fmac_f32_e32 v10, v111, v9
	v_fmac_f32_e32 v0, v95, v9
	s_setprio 0
	v_lshlrev_b32_e32 v2, 1, v235
	v_bfe_u32 v3, v16, 16, 1
	v_lshlrev_b32_e32 v4, 9, v234
	v_add3_u32 v3, v16, v3, s15
	v_add3_u32 v2, s18, v2, v4
	ds_write_b16_d16_hi v2, v3 offset:33792
	v_bfe_u32 v3, v32, 16, 1
	v_add3_u32 v3, v32, v3, s15
	ds_write_b16_d16_hi v2, v3 offset:33856
	v_bfe_u32 v3, v17, 16, 1
	v_add3_u32 v3, v17, v3, s15
	ds_write_b16_d16_hi v2, v3 offset:33920
	v_bfe_u32 v3, v33, 16, 1
	v_add3_u32 v3, v33, v3, s15
	ds_write_b16_d16_hi v2, v3 offset:33984
	v_bfe_u32 v3, v18, 16, 1
	v_add3_u32 v3, v18, v3, s15
	ds_write_b16_d16_hi v2, v3 offset:34048
	v_bfe_u32 v3, v34, 16, 1
	v_add3_u32 v3, v34, v3, s15
	ds_write_b16_d16_hi v2, v3 offset:34112
	v_bfe_u32 v3, v19, 16, 1
	v_add3_u32 v3, v19, v3, s15
	ds_write_b16_d16_hi v2, v3 offset:34176
	v_bfe_u32 v3, v35, 16, 1
	v_add3_u32 v3, v35, v3, s15
	ds_write_b16_d16_hi v2, v3 offset:34240
	v_bfe_u32 v3, v20, 16, 1
	v_add3_u32 v3, v20, v3, s15
	ds_write_b16_d16_hi v2, v3 offset:34816
	v_bfe_u32 v3, v36, 16, 1
	v_add3_u32 v3, v36, v3, s15
	ds_write_b16_d16_hi v2, v3 offset:34880
	v_bfe_u32 v3, v21, 16, 1
	v_add3_u32 v3, v21, v3, s15
	ds_write_b16_d16_hi v2, v3 offset:34944
	v_bfe_u32 v3, v37, 16, 1
	v_add3_u32 v3, v37, v3, s15
	ds_write_b16_d16_hi v2, v3 offset:35008
	v_bfe_u32 v3, v22, 16, 1
	v_add3_u32 v3, v22, v3, s15
	ds_write_b16_d16_hi v2, v3 offset:35072
	v_bfe_u32 v3, v38, 16, 1
	v_add3_u32 v3, v38, v3, s15
	ds_write_b16_d16_hi v2, v3 offset:35136
	v_bfe_u32 v3, v23, 16, 1
	v_add3_u32 v3, v23, v3, s15
	ds_write_b16_d16_hi v2, v3 offset:35200
	v_bfe_u32 v3, v39, 16, 1
	v_add3_u32 v3, v39, v3, s15
	ds_write_b16_d16_hi v2, v3 offset:35264
	v_bfe_u32 v3, v24, 16, 1
	v_add3_u32 v3, v24, v3, s15
	ds_write_b16_d16_hi v2, v3 offset:35840
	v_bfe_u32 v3, v40, 16, 1
	v_add3_u32 v3, v40, v3, s15
	ds_write_b16_d16_hi v2, v3 offset:35904
	v_bfe_u32 v3, v25, 16, 1
	v_add3_u32 v3, v25, v3, s15
	ds_write_b16_d16_hi v2, v3 offset:35968
	v_bfe_u32 v3, v31, 16, 1
	v_add3_u32 v3, v31, v3, s15
	ds_write_b16_d16_hi v2, v3 offset:36032
	v_bfe_u32 v3, v26, 16, 1
	v_add3_u32 v3, v26, v3, s15
	ds_write_b16_d16_hi v2, v3 offset:36096
	v_bfe_u32 v3, v30, 16, 1
	v_add3_u32 v3, v30, v3, s15
	ds_write_b16_d16_hi v2, v3 offset:36160
	v_bfe_u32 v3, v27, 16, 1
	v_add3_u32 v3, v27, v3, s15
	ds_write_b16_d16_hi v2, v3 offset:36224
	v_bfe_u32 v3, v29, 16, 1
	v_add3_u32 v3, v29, v3, s15
	ds_write_b16_d16_hi v2, v3 offset:36288
	v_bfe_u32 v3, v28, 16, 1
	v_add3_u32 v3, v28, v3, s15
	ds_write_b16_d16_hi v2, v3 offset:36864
	v_bfe_u32 v3, v15, 16, 1
	v_add3_u32 v3, v15, v3, s15
	ds_write_b16_d16_hi v2, v3 offset:36928
	v_bfe_u32 v3, v14, 16, 1
	v_add3_u32 v3, v14, v3, s15
	ds_write_b16_d16_hi v2, v3 offset:36992
	v_bfe_u32 v3, v13, 16, 1
	v_add3_u32 v3, v13, v3, s15
	ds_write_b16_d16_hi v2, v3 offset:37056
	v_bfe_u32 v3, v12, 16, 1
	v_add3_u32 v3, v12, v3, s15
	ds_write_b16_d16_hi v2, v3 offset:37120
	v_bfe_u32 v3, v11, 16, 1
	v_add3_u32 v3, v11, v3, s15
	ds_write_b16_d16_hi v2, v3 offset:37184
	v_bfe_u32 v3, v10, 16, 1
	v_add3_u32 v3, v10, v3, s15
	ds_write_b16_d16_hi v2, v3 offset:37248
	v_bfe_u32 v3, v0, 16, 1
	v_add3_u32 v0, v0, v3, s15
	ds_write_b16_d16_hi v2, v0 offset:37312
	s_waitcnt lgkmcnt(0)
	ds_read_b32 v0, v1 offset:464
	s_or_b32 s4, s27, s33
	s_or_b32 s4, s12, s4
	s_lshl_b32 s4, s4, 11
	v_ashrrev_i32_e32 v6, 3, v247
	s_waitcnt lgkmcnt(0)
	v_readfirstlane_b32 s2, v0
	ds_read_b32 v0, v1 offset:468
	s_add_u32 s4, s2, s4
	v_ashrrev_i32_e32 v7, 31, v6
	v_lshlrev_b64 v[10:11], 11, v[6:7]
	v_mov_b32_e32 v220, 1
	s_waitcnt lgkmcnt(0)
	v_readfirstlane_b32 s3, v0
	s_addc_u32 s5, s3, 0
	s_lshl_b64 s[2:3], s[10:11], 1
	v_lshlrev_b32_e32 v0, 1, v237
	s_add_u32 s2, s4, s2
	v_and_b32_e32 v0, 0x70, v0
	s_addc_u32 s3, s5, s3
	v_add_u32_e32 v12, s18, v0
	v_lshl_add_u64 v[2:3], s[2:3], 0, v[0:1]
	s_mov_b64 s[2:3], 0x20700000
	v_lshl_add_u32 v0, v6, 7, v12
	v_lshl_add_u64 v[8:9], v[2:3], 0, s[2:3]
	ds_read_b128 v[2:5], v0 offset:33792
	v_lshl_add_u64 v[10:11], v[8:9], 0, v[10:11]
	s_mov_b64 s[2:3], 0
	v_mov_b32_e32 v221, 0x358637bd
	v_mov_b32_e32 v222, 0x7f800000
	s_waitcnt lgkmcnt(0)
	global_store_dwordx4 v[10:11], v[2:5], off
	v_add_u32_e32 v10, 8, v6
	v_lshl_add_u32 v0, v10, 7, v12
	ds_read_b128 v[2:5], v0 offset:33792
	v_ashrrev_i32_e32 v11, 31, v10
	v_lshlrev_b64 v[10:11], 11, v[10:11]
	v_lshl_add_u64 v[10:11], v[8:9], 0, v[10:11]
	v_mov_b32_e32 v223, v252
	s_waitcnt lgkmcnt(0)
	global_store_dwordx4 v[10:11], v[2:5], off
	v_add_u32_e32 v10, 16, v6
	v_lshl_add_u32 v0, v10, 7, v12
	ds_read_b128 v[2:5], v0 offset:33792
	v_ashrrev_i32_e32 v11, 31, v10
	v_lshlrev_b64 v[10:11], 11, v[10:11]
	v_add_u32_e32 v6, 24, v6
	v_lshl_add_u64 v[10:11], v[8:9], 0, v[10:11]
	v_lshl_add_u32 v0, v6, 7, v12
	s_waitcnt lgkmcnt(0)
	global_store_dwordx4 v[10:11], v[2:5], off
	ds_read_b128 v[2:5], v0 offset:33792
	v_ashrrev_i32_e32 v7, 31, v6
	v_lshlrev_b64 v[6:7], 11, v[6:7]
	v_lshl_add_u64 v[6:7], v[8:9], 0, v[6:7]
	s_waitcnt vmcnt(4)
	v_mov_b32_e32 v224, 0xff800000
	v_mov_b64_e32 v[226:227], 0x100
	s_waitcnt vmcnt(3)
	v_mov_b64_e32 v[228:229], 0xff
	s_waitcnt lgkmcnt(0)
	global_store_dwordx4 v[6:7], v[2:5], off
	s_barrier

; #define LAS __attribute__((address_space(3)))
; __device__ __forceinline__ float sigmoidf_(float x) { return 1.0f / (1.0f + __expf(-x)); }
; __device__ __forceinline__ int hw_lane() { int ln; asm volatile("v_mbcnt_lo_u32_b32 %0, -1, 0\n\tv_mbcnt_hi_u32_b32 %0, -1, %0" : "=v"(ln)); return ln; }
; __device__ __forceinline__ void nsa_unit(const Ctx& c, int l, int b, int n, int qt) {
;     LAS unsigned char* lds = c.lds; const int lane = c.lane, wid = c.wave, r32 = lane & 31, hi = lane >> 5, g = wid >> 1, th = wid & 1;
;     const int tq = th * 32 + r32, t0 = qt * 64, t = t0 + tq, hq = n * 4 + g;
;     if (wid >= 4) __builtin_amdgcn_s_setprio(1);
;     const float sl2 = exp2f(-(float)(hq + 1)) * LOG2E;
;     LAS float* wsf = (LAS float*)(lds + NL_WSF + wid * 256); LAS float* imp = (LAS float*)(lds + NL_IMP); LAS unsigned long long* maskb = (LAS unsigned long long*)(lds + NL_MASK);
;     const bf16* H = (const bf16*)(AWS + WS_H); const float* HS = (const float*)(AWS + WS_HS);
;     const size_t rowbase = (size_t)b * SEQ;
;     bf16x8v qr[4];
; #pragma unroll
;     for (int d0 = 0; d0 < 4; ++d0) qr[d0] = __builtin_nontemporal_load((const bf16x8v*)(H + (rowbase + t) * HW + HQ + hq * 64 + d0 * 16 + hi * 8));
;     const float* gp = HS + (rowbase + t) * 64 + hq * 3;
;     const float gate0 = sigmoidf_(gp[0]), gate1 = sigmoidf_(gp[1]), gate2 = sigmoidf_(gp[2]);
;     u32x4 kreg, vreg;
;     f32x16 of0, of1;
;     {
;         const bf16* KCb = (const bf16*)(AWS + WS_KCB) + ((size_t)b * 128 * 2 + n) * 64; const bf16* VCb = (const bf16*)(AWS + WS_VCB) + ((size_t)b * 128 * 2 + n) * 64;
;         const bool two = (t0 + 63 >= 64 * 32 + 31);
;         NSA_LOADT(KCb, VCb, 128); NSA_STORET(0);
;         if (two) { NSA_LOADT(KCb + 64 * 128, VCb + 64 * 128, 128); NSA_STORET(1); }
;     ...
;         for (;;) {
;             if (c.wave == 0 && hw_lane() == 0) { unsigned* head = c.ctl + (l ? CW_U1 : CW_U0) + rep * 1024; *slot = __hip_atomic_fetch_add(head, 1u, __ATOMIC_RELAXED, __HIP_MEMORY_SCOPE_AGENT); }
;             __syncthreads();
;             const unsigned u = *slot;
;             __syncthreads();
;             if (u >= 512u) break;
;             Ctx cu = c; { int ln = hw_lane(); asm volatile("" : "+v"(ln)); cu.lane = ln; cu.tid = cu.wave * 64 + ln; }
;             nsa_unit(cu, l, (int)(u >> 1) & 3, (int)u & 1, 63 - (int)(u >> 3));
.LBB0_1299:
	s_andn2_b64 vcc, exec, s[38:39]
	s_cbranch_vccnz .LBB0_1305
	v_mbcnt_lo_u32_b32 v0, -1, 0
	v_mbcnt_hi_u32_b32 v0, -1, v0
	v_cmp_eq_u32_e32 vcc, 0, v0
	s_and_saveexec_b64 s[2:3], vcc
	v_mov_b32_e32 v0, s32
	ds_write_b32 v1, v0 offset:64
	s_or_b64 exec, exec, s[2:3]
.LBB0_1305:
	s_waitcnt vmcnt(0) lgkmcnt(0)
	s_barrier
	ds_read_b32 v0, v1 offset:64
	s_movk_i32 s2, 0x1ff
	s_waitcnt lgkmcnt(0)
	s_barrier
	v_cmp_lt_u32_e32 vcc, s2, v0
	v_readfirstlane_b32 s9, v0
	s_mov_b64 s[2:3], -1
	s_cbranch_vccnz .LBB0_1298
	s_andn2_b64 vcc, exec, s[38:39]
	s_cbranch_vccnz .Lnq_skip1
	v_mbcnt_lo_u32_b32 v40, -1, 0
	v_mbcnt_hi_u32_b32 v40, -1, v40
	v_cmp_eq_u32_e32 vcc, 0, v40
	s_and_saveexec_b64 s[2:3], vcc
	v_readlane_b32 s6, v255, 16
	v_readlane_b32 s7, v255, 17
	v_mov_b32_e32 v41, 1
	s_nop 4
	global_atomic_add v40, v1, v41, s[6:7] sc0
	s_or_b64 exec, exec, s[2:3]
.Lnq_skip1:
	v_readlane_b32 s2, v255, 12
	v_readlane_b32 s3, v255, 13
	v_mbcnt_lo_u32_b32 v247, -1, 0
	v_mbcnt_hi_u32_b32 v247, -1, v247
	s_andn2_b64 vcc, exec, s[2:3]
	s_cbranch_vccnz .LBB0_1308
	s_setprio 1
.LBB0_1308:
	ds_read_b32 v0, v1 offset:464
	s_and_b32 s8, s9, 1
	ds_read_b32 v2, v1 offset:468
	s_lshl_b32 s17, s8, 2
	v_readlane_b32 s2, v254, 62
	s_lshr_b32 s13, s9, 3
	s_add_i32 s17, s17, s2
	s_waitcnt lgkmcnt(1)
	v_readfirstlane_b32 s2, v0
	ds_read_b32 v0, v1 offset:464
	ds_read_b32 v3, v1 offset:468
	s_sub_i32 s46, 63, s13
	s_bfe_u32 s16, s9, 0x20001
	v_and_b32_e32 v235, 31, v247
	s_lshl_b32 s27, s46, 6
	v_or_b32_e32 v154, s33, v235
	s_waitcnt lgkmcnt(2)
	v_readfirstlane_b32 s3, v2
	s_add_u32 s44, s2, 0xfd00000
	v_or_b32_e32 v155, s27, v154
	s_addc_u32 s45, s3, 0
	s_lshl_b32 s12, s16, 12
	v_ashrrev_i32_e32 v234, 5, v247
	s_waitcnt lgkmcnt(1)
	v_readfirstlane_b32 s2, v0
	s_waitcnt lgkmcnt(0)
	v_readfirstlane_b32 s3, v3
	v_or_b32_e32 v0, s12, v155
	v_mov_b64_e32 v[2:3], s[44:45]
	s_movk_i32 s4, 0x1c00
	s_lshl_b32 s10, s17, 6
	v_mad_u64_u32 v[2:3], s[4:5], v0, s4, v[2:3]
	s_ashr_i32 s11, s10, 31
	v_lshlrev_b32_e32 v66, 3, v234
	v_lshl_add_u64 v[2:3], s[10:11], 1, v[2:3]
	v_ashrrev_i32_e32 v67, 31, v66
	v_lshl_add_u64 v[2:3], v[66:67], 1, v[2:3]
	v_lshlrev_b32_e32 v0, 8, v0
	global_load_dwordx4 v[176:179], v[2:3], off nt
	global_load_dwordx4 v[180:183], v[2:3], off offset:32 nt
	global_load_dwordx4 v[184:187], v[2:3], off offset:64 nt
	global_load_dwordx4 v[188:191], v[2:3], off offset:96 nt
	v_lshl_add_u64 v[2:3], s[2:3], 0, v[0:1]
	s_mul_i32 s2, s17, 3
	s_ashr_i32 s3, s2, 31
	v_lshl_add_u64 v[2:3], s[2:3], 2, v[2:3]
	s_mov_b32 s2, 0x16f00000
	v_add_co_u32_e32 v2, vcc, s2, v2
	s_lshl_b32 s4, s8, 7
	s_nop 0
	v_addc_co_u32_e32 v3, vcc, 0, v3, vcc
	global_load_dwordx3 v[230:232], v[2:3], off
	ds_read_b32 v0, v1 offset:464
	ds_read_b32 v2, v1 offset:468
	s_lshl_b32 s5, s16, 15
	s_or_b32 s4, s5, s4
	v_mov_b32_e32 v6, v247
	s_waitcnt lgkmcnt(1)
	v_readfirstlane_b32 s2, v0
	s_waitcnt lgkmcnt(0)
	v_readfirstlane_b32 s3, v2
	ds_read_b32 v0, v1 offset:464
	ds_read_b32 v2, v1 offset:468
	s_add_u32 s2, s2, s4
	s_addc_u32 s3, s3, 0
	s_add_u32 s6, s2, 0x3a400000
	s_addc_u32 s7, s3, 0
	s_waitcnt lgkmcnt(1)
	v_readfirstlane_b32 s2, v0
	s_waitcnt lgkmcnt(0)
	v_readfirstlane_b32 s3, v2
	v_lshl_add_u32 v0, v6, 7, s1
	s_add_u32 s2, s2, s4
	v_lshl_add_u64 v[2:3], v[0:1], 1, s[6:7]
	v_lshrrev_b32_e32 v0, 2, v6
	s_addc_u32 s3, s3, 0
	v_add_u32_e32 v0, s22, v0
	s_add_u32 s4, s2, 0x3a500000
	v_lshl_add_u32 v0, v0, 7, s23
	v_lshlrev_b32_e32 v6, 3, v6
	s_addc_u32 s5, s3, 0
	v_and_or_b32 v0, v6, 24, v0
	global_load_dwordx4 v[2:5], v[2:3], off
	v_lshl_add_u64 v[6:7], v[0:1], 1, s[4:5]
	global_load_dwordx4 v[6:9], v[6:7], off
	s_cmpk_lt_u32 s9, 0x100
	v_lshlrev_b32_e32 v113, 4, v247
	s_cselect_b64 s[2:3], -1, 0
	s_cmpk_gt_u32 s9, 0xff
	v_add_u32_e32 v251, s26, v113
	s_waitcnt vmcnt(1)
	ds_write_b128 v251, v[2:5] offset:1024
	s_waitcnt vmcnt(0)
	ds_write_b128 v251, v[6:9] offset:17408
	v_readfirstlane_b32 s32, v40
	s_cbranch_scc1 .LBB0_1310
	v_mov_b32_e32 v6, v247
	s_nop 0
	v_lshl_add_u32 v0, v6, 7, s1
	v_lshl_add_u64 v[2:3], v[0:1], 1, s[6:7]
	v_lshrrev_b32_e32 v0, 2, v6
	v_add_u32_e32 v0, s22, v0
	v_lshl_add_u32 v0, v0, 7, s23
	v_lshlrev_b32_e32 v6, 3, v6
	v_add_co_u32_e32 v2, vcc, 0x4000, v2
	v_and_or_b32 v0, v6, 24, v0
	s_nop 0
	v_addc_co_u32_e32 v3, vcc, 0, v3, vcc
	v_lshl_add_u64 v[6:7], v[0:1], 1, s[4:5]
	v_add_co_u32_e32 v6, vcc, 0x4000, v6
	global_load_dwordx4 v[2:5], v[2:3], off
	s_nop 0
	v_addc_co_u32_e32 v7, vcc, 0, v7, vcc
	global_load_dwordx4 v[6:9], v[6:7], off
	s_waitcnt vmcnt(1)
	ds_write_b128 v251, v[2:5] offset:9216
	s_waitcnt vmcnt(0)
	ds_write_b128 v251, v[6:9] offset:25600
